# stack: attention counted lgkmcnt waits + lagging waves issue K/V DMA after deferred PV + hand-written scan compute block
# speedup vs baseline: 1.0178x; 1.0178x over previous
.Lattn_lag:
	v_lshl_add_u32 v0, s52, 14, v234
	ds_read_b128 v[130:133], v0 offset:49152
	ds_read_b128 v[134:137], v0 offset:50176
	ds_read_b128 v[138:141], v0 offset:51200
	ds_read_b128 v[142:145], v0 offset:52224
	s_waitcnt lgkmcnt(3)
	v_mfma_f32_16x16x32_bf16 v[110:113], v[130:133], v[114:117], v[110:113]
	v_mfma_f32_16x16x32_bf16 v[30:33], v[130:133], v[122:125], v[30:33]
	s_waitcnt lgkmcnt(2)
	v_mfma_f32_16x16x32_bf16 v[110:113], v[134:137], v[118:121], v[110:113]
	v_mfma_f32_16x16x32_bf16 v[30:33], v[134:137], v[126:129], v[30:33]
	ds_read_b128 v[130:133], v0 offset:53248
	ds_read_b128 v[134:137], v0 offset:54272
	s_waitcnt lgkmcnt(2)
	v_mfma_f32_16x16x32_bf16 v[106:109], v[138:141], v[114:117], v[106:109]
	v_mfma_f32_16x16x32_bf16 v[26:29], v[138:141], v[122:125], v[26:29]
	v_mfma_f32_16x16x32_bf16 v[106:109], v[142:145], v[118:121], v[106:109]
	v_mfma_f32_16x16x32_bf16 v[26:29], v[142:145], v[126:129], v[26:29]
	ds_read_b128 v[138:141], v0 offset:55296
	ds_read_b128 v[142:145], v0 offset:56320
	s_waitcnt lgkmcnt(2)
	v_mfma_f32_16x16x32_bf16 v[102:105], v[130:133], v[114:117], v[102:105]
	v_mfma_f32_16x16x32_bf16 v[22:25], v[130:133], v[122:125], v[22:25]
	v_mfma_f32_16x16x32_bf16 v[102:105], v[134:137], v[118:121], v[102:105]
	v_mfma_f32_16x16x32_bf16 v[22:25], v[134:137], v[126:129], v[22:25]
	ds_read_b128 v[130:133], v0 offset:57344
	ds_read_b128 v[134:137], v0 offset:58368
	s_waitcnt lgkmcnt(2)
	v_mfma_f32_16x16x32_bf16 v[98:101], v[138:141], v[114:117], v[98:101]
	v_mfma_f32_16x16x32_bf16 v[18:21], v[138:141], v[122:125], v[18:21]
	v_mfma_f32_16x16x32_bf16 v[98:101], v[142:145], v[118:121], v[98:101]
	v_mfma_f32_16x16x32_bf16 v[18:21], v[142:145], v[126:129], v[18:21]
	ds_read_b128 v[138:141], v0 offset:59392
	ds_read_b128 v[142:145], v0 offset:60416
	s_waitcnt lgkmcnt(2)
	v_mfma_f32_16x16x32_bf16 v[90:93], v[130:133], v[114:117], v[90:93]
	v_mfma_f32_16x16x32_bf16 v[14:17], v[130:133], v[122:125], v[14:17]
	v_mfma_f32_16x16x32_bf16 v[90:93], v[134:137], v[118:121], v[90:93]
	v_mfma_f32_16x16x32_bf16 v[14:17], v[134:137], v[126:129], v[14:17]
	ds_read_b128 v[130:133], v0 offset:61440
	ds_read_b128 v[134:137], v0 offset:62464
	s_waitcnt lgkmcnt(2)
	v_mfma_f32_16x16x32_bf16 v[70:73], v[138:141], v[114:117], v[70:73]
	v_mfma_f32_16x16x32_bf16 v[10:13], v[138:141], v[122:125], v[10:13]
	v_mfma_f32_16x16x32_bf16 v[70:73], v[142:145], v[118:121], v[70:73]
	v_mfma_f32_16x16x32_bf16 v[10:13], v[142:145], v[126:129], v[10:13]
	ds_read_b128 v[138:141], v0 offset:63488
	ds_read_b128 v[142:145], v0 offset:64512
	s_waitcnt lgkmcnt(2)
	v_mfma_f32_16x16x32_bf16 v[38:41], v[130:133], v[114:117], v[38:41]
	v_mfma_f32_16x16x32_bf16 v[6:9], v[130:133], v[122:125], v[6:9]
	v_mfma_f32_16x16x32_bf16 v[38:41], v[134:137], v[118:121], v[38:41]
	v_mfma_f32_16x16x32_bf16 v[6:9], v[134:137], v[126:129], v[6:9]
	s_waitcnt lgkmcnt(0)
	v_mfma_f32_16x16x32_bf16 v[34:37], v[138:141], v[114:117], v[34:37]
	v_mfma_f32_16x16x32_bf16 v[2:5], v[138:141], v[122:125], v[2:5]
	v_mfma_f32_16x16x32_bf16 v[34:37], v[142:145], v[118:121], v[34:37]
	v_mfma_f32_16x16x32_bf16 v[2:5], v[142:145], v[126:129], v[2:5]
	s_cmp_ge_u32 s53, s43
	s_cbranch_scc1 .Lattn_lag_nodma
	s_bitcmp1_b32 s53, 0
	s_cselect_b32 s54, 0x6000, 0
	s_add_i32 s54, s54, 0
	v_lshl_add_u64 v[130:131], v[180:181], 0, v[166:167]
	s_add_i32 m0, s54, s23
	s_nop 0
	global_load_lds_dwordx4 v[130:131], off
	v_lshl_add_u64 v[130:131], v[178:179], 0, v[166:167]
	s_add_i32 m0, s54, s24
	s_nop 0
	global_load_lds_dwordx4 v[130:131], off
	s_add_i32 m0, s54, s25
	s_lshl_b32 s54, s44, 14
	s_add_i32 s54, s54, 0
	v_lshl_add_u64 v[130:131], v[176:177], 0, v[166:167]
	s_add_i32 s56, s54, s23
	global_load_lds_dwordx4 v[130:131], off
	v_lshl_add_u64 v[130:131], v[182:183], 0, v[166:167]
	s_add_i32 m0, s56, 0xc000
	s_add_i32 s54, s54, s24
	global_load_lds_dwordx4 v[130:131], off
	v_lshl_add_u64 v[130:131], v[184:185], 0, v[166:167]
	s_add_i32 m0, s54, 0xc000
	s_nop 0
	global_load_lds_dwordx4 v[130:131], off
